# retention prompt loop: next chunk's Q/K LDS staging issued after the intra MFMAs (overlaps output stage) instead of after the end-of-chunk barrier
# baseline (speedup 1.0000x reference)
; template <int DK, int MODE>
; __device__ void rec_prompt_item(const Params& p, const int item, unsigned char* smem) {
;     ...
; #pragma unroll
;   for (int i = 0; i < NQ; ++i) {
;     const int c_ = tid + NTHR * i;
;     qoff[i] = (unsigned)(((c_ / CPR) * sstride + qcol + (c_ % CPR) * 8) * 2);
;   }
;   const unsigned voffv = (unsigned)((vrow * sstride + vcol + vkc * 8) * 2);
; #pragma unroll
;   for (int r = 0; r < 4; ++r) {
;     goff[r] = (unsigned)(((16 * fi + 4 * g + r) * PROJ_LD + gcol + 16 * fe0 + l15) * 2);
;     aoff[r] = (unsigned)(((16 * fi + 4 * g + r) * 2048 + ((MODE == 0) ? (h * 512 + s * 64) : (h * 64)) + 16 * fe0 + l15) * 2);
;   }
;   const int kdelta = (kcol - qcol) * 2;
;     ...
;   f32x4 S[MF][4];
; #pragma unroll
;   for (int i = 0; i < MF; ++i)
; #pragma unroll
;     for (int j = 0; j < 4; ++j) S[i][j] = (f32x4){0.f, 0.f, 0.f, 0.f};
;     ...
; #pragma unroll
;     for (int i = 0; i < NQ; ++i) {
;       int cc = tid + NTHR * i, rr = cc / CPR, kc = cc % CPR;
;       *(u32x4*)(Qs + rr * QS + kc * 16) = rq[par][i];
;       *(u32x4*)(Ks + rr * QS + kc * 16) = rk[par][i];
;     }
.LBB0_418:
	s_bfe_u32 s41, s38, 0x20006
	v_cvt_f32_ubyte0_e32 v0, s41
	v_sub_f32_e32 v0, 0xc0a00000, v0
	v_cmp_gt_f32_e64 s[20:21], s35, v0
	s_bfe_u32 s43, s38, 0x30003
	s_lshl_b32 s44, s41, 9
	v_cndmask_b32_e64 v1, 0, v179, s[20:21]
	v_add_f32_e32 v0, v0, v1
	s_lshl_b32 s39, s43, 6
	v_exp_f32_e32 v0, v0
	s_and_b32 s40, s38, 7
	s_or_b32 s45, s44, s39
	s_and_b64 s[20:21], s[20:21], exec
	s_cselect_b32 s20, 0xffffffc0, 0
	v_ldexp_f32 v0, v0, s20
	v_sub_f32_e32 v36, 1.0, v0
	v_cmp_gt_f32_e64 s[20:21], s37, v36
	v_or_b32_e32 v0, s45, v175
	v_add_lshl_u32 v124, v0, v151, 1
	v_cndmask_b32_e64 v37, 0, v180, s[20:21]
	s_and_b64 s[20:21], s[20:21], exec
	s_cselect_b32 s46, 32, 0
	s_lshl_b32 s42, s40, 11
	v_add_lshl_u32 v126, v0, v152, 1
	v_add_lshl_u32 v128, v0, v153, 1
	v_add_lshl_u32 v130, v0, v154, 1
	v_or_b32_e32 v0, s39, v147
	s_mul_i32 s20, s40, 0x1840000
	v_or3_b32 v1, s44, v95, v0
	v_or3_b32 v0, v0, s44, v156
	s_add_u32 s20, s30, s20
	v_add_u32_e32 v98, s44, v88
	v_add_u32_e32 v122, s44, v94
	s_waitcnt vmcnt(48)
	v_add_u32_e32 v28, s45, v89
	v_lshlrev_b32_e32 v1, 2, v1
	v_lshlrev_b32_e32 v0, 2, v0
	s_addc_u32 s21, s31, 0
	v_add_u32_e32 v118, s44, v90
	v_add_u32_e32 v120, s44, v92
	global_load_dword v117, v1, s[92:93]
	global_load_dword v199, v0, s[92:93]
	s_nop 0
	global_load_dwordx4 v[0:3], v98, s[20:21] offset:2048
	global_load_dwordx4 v[4:7], v98, s[20:21]
	global_load_dwordx4 v[8:11], v118, s[20:21] offset:2048
	global_load_dwordx4 v[12:15], v118, s[20:21]
	global_load_dwordx4 v[16:19], v120, s[20:21] offset:2048
	global_load_dwordx4 v[20:23], v120, s[20:21]
	global_load_dwordx4 v[24:27], v122, s[20:21] offset:2048
	v_lshl_or_b32 v132, v28, 1, v155
	global_load_dwordx4 v[32:35], v122, s[20:21]
	global_load_dwordx4 v[28:31], v132, s[20:21]
	global_load_ushort v208, v124, s[20:21]
	global_load_ushort v207, v126, s[20:21]
	global_load_ushort v206, v128, s[20:21]
	global_load_ushort v205, v130, s[20:21]
	global_load_ushort v204, v124, s[20:21] offset:32
	global_load_ushort v203, v126, s[20:21] offset:32
	global_load_ushort v202, v128, s[20:21] offset:32
	global_load_ushort v201, v130, s[20:21] offset:32
	v_ldexp_f32 v36, v36, s46
	v_log_f32_e32 v36, v36
	s_lshl_b32 s20, s41, 4
	s_lshl_b32 s21, s43, 1
	s_or_b32 s20, s20, s21
	v_sub_f32_e32 v36, v36, v37
	v_or_b32_e32 v37, s45, v171
	v_lshlrev_b32_e32 v134, 1, v37
	v_or_b32_e32 v37, s45, v172
	v_lshlrev_b32_e32 v136, 1, v37
	v_or_b32_e32 v37, s45, v173
	v_lshlrev_b32_e32 v138, 1, v37
	v_or_b32_e32 v37, s45, v174
	v_lshlrev_b32_e32 v140, 1, v37
	v_mul_f32_e32 v37, v36, v157
	v_fma_f32 v37, v36, s36, -v37
	v_exp_f32_e32 v142, v37
	v_or_b32_e32 v37, s20, v150
	v_mul_f32_e32 v200, v36, v162
	v_lshlrev_b32_e32 v36, 2, v37
	v_mov_b32_e32 v37, v99
	v_mov_b32_e32 v119, v99
	v_mov_b32_e32 v121, v99
	v_mov_b32_e32 v123, v99
	v_mov_b32_e32 v133, v99
	v_mov_b32_e32 v125, v99
	v_mov_b32_e32 v127, v99
	v_mov_b32_e32 v129, v99
	v_mov_b32_e32 v131, v99
	v_mov_b32_e32 v135, v99
	v_mov_b32_e32 v137, v99
	v_mov_b32_e32 v139, v99
	v_mov_b32_e32 v141, v99
	v_lshl_add_u64 v[144:145], s[22:23], 0, v[36:37]
	v_mov_b32_e32 v143, v142
	s_mov_b32 s43, 0
	v_mov_b32_e32 v36, v99
	v_mov_b32_e32 v38, v99
	v_mov_b32_e32 v39, v99
	v_mov_b32_e32 v40, v99
	v_mov_b32_e32 v41, v99
	v_mov_b32_e32 v42, v99
	v_mov_b32_e32 v43, v99
	v_mov_b32_e32 v44, v99
	v_mov_b32_e32 v45, v99
	v_mov_b32_e32 v46, v99
	v_mov_b32_e32 v47, v99
	v_mov_b32_e32 v48, v99
	v_mov_b32_e32 v49, v99
	v_mov_b32_e32 v50, v99
	v_mov_b32_e32 v51, v99
	v_mov_b32_e32 v52, v99
	v_mov_b32_e32 v53, v99
	v_mov_b32_e32 v54, v99
	v_mov_b32_e32 v55, v99
	v_mov_b32_e32 v56, v99
	v_mov_b32_e32 v57, v99
	v_mov_b32_e32 v58, v99
	v_mov_b32_e32 v59, v99
	v_mov_b32_e32 v60, v99
	v_mov_b32_e32 v61, v99
	v_mov_b32_e32 v62, v99
	v_mov_b32_e32 v63, v99
	v_mov_b32_e32 v64, v99
	v_mov_b32_e32 v65, v99
	v_mov_b32_e32 v66, v99
	v_mov_b32_e32 v67, v99
	s_waitcnt vmcnt(0)
	ds_write_b128 v181, v[4:7]
	ds_write_b128 v181, v[0:3] offset:34816
	ds_write_b128 v182, v[12:15]
	ds_write_b128 v182, v[8:11] offset:34816
	ds_write_b128 v183, v[20:23]
	ds_write_b128 v183, v[16:19] offset:34816
	ds_write_b128 v184, v[32:35]
	ds_write_b128 v184, v[24:27] offset:34816
	s_branch .LBB0_420

; template <int DK, int MODE>
; __device__ void rec_prompt_item(const Params& p, const int item, unsigned char* smem) {
;     ...
;     {
;       const u32x4 rvv = rv[par];
;       *(u32x4*)(Vs + vrow * VS + vkc * 16) = rvv;
;       float cj, uj, cl;
;       if (MODE == 0) { cj = (float)(vrow + 1) * lg; uj = 1.f; cl = 64.f * lg; } else { cj = pcj[par]; uj = puj[par]; cl = pclast[par]; }
;       const float wj = uj * ex2(cl - cj);
;       u32x4 o;
;       o.x = pack2(bf2f((u16)(rvv.x & 0xffff)) * wj, bf2f((u16)(rvv.x >> 16)) * wj);
;       o.y = pack2(bf2f((u16)(rvv.y & 0xffff)) * wj, bf2f((u16)(rvv.y >> 16)) * wj);
;       o.z = pack2(bf2f((u16)(rvv.z & 0xffff)) * wj, bf2f((u16)(rvv.z >> 16)) * wj);
;       o.w = pack2(bf2f((u16)(rvv.w & 0xffff)) * wj, bf2f((u16)(rvv.w >> 16)) * wj);
;       *(u32x4*)(Vts + vrow * VS + vkc * 16) = o;
;     }
;     if (tid < 64) {
;       if (MODE == 0) { cumS[tid] = (float)(tid + 1) * lg; uS[tid] = 1.f; } else { cumS[tid] = pct[par]; uS[tid] = put[par]; }
;     }
; #pragma unroll
;     for (int mf = 0; mf < MF; ++mf)
; #pragma unroll
;       for (int nf = 0; nf < 4; ++nf) {
;         u32x2 o;
;         o.x = pack2(S[mf][nf][0], S[mf][nf][1]);
;         o.y = pack2(S[mf][nf][2], S[mf][nf][3]);
;         *(u32x2*)(STs + (16 * nf + l15) * QS + (dw + 16 * mf + 4 * g) * 2) = o;
;       }
;     u16 gzc[2][4];
; #pragma unroll
;     for (int x = 0; x < 2; ++x)
; #pragma unroll
;       for (int r = 0; r < 4; ++r) gzc[x][r] = gz[par][x][r];
;     __syncthreads();
;     if (c + NSET < 32) PF_ISSUE(par, r0 + 64 * NSET)
;     f32x4 sc[2], cr[2];
; #pragma unroll
;     for (int x = 0; x < 2; ++x) { sc[x] = (f32x4){0.f, 0.f, 0.f, 0.f}; cr[x] = (f32x4){0.f, 0.f, 0.f, 0.f}; }
; #pragma unroll KUNR
;     for (int ks = 0; ks < KS; ++ks) {
;       const bf16x8 a = *(const bf16x8*)(Qs + (16 * fi + l15) * QS + ks * 64 + g * 16);
;       bf16x8 bk[2], bs[2];
; #pragma unroll
;       for (int x = 0; x < 2; ++x) {
;         bk[x] = *(const bf16x8*)(Ks + (16 * (fe0 + x) + l15) * QS + ks * 64 + g * 16);
;         bs[x] = *(const bf16x8*)(STs + (16 * (fe0 + x) + l15) * QS + ks * 64 + g * 16);
;       }
; #pragma unroll
;       for (int x = 0; x < 2; ++x) {
;         sc[x] = __builtin_amdgcn_mfma_f32_16x16x32_bf16(a, bk[x], sc[x], 0, 0, 0);
;         cr[x] = __builtin_amdgcn_mfma_f32_16x16x32_bf16(a, bs[x], cr[x], 0, 0, 0);
;       }
;     }
.LBB0_420:
	s_waitcnt vmcnt(8)
	ds_write_b128 v185, v[28:31]
	v_and_b32_e32 v1, 0xffff0000, v28
	v_lshlrev_b32_e32 v0, 16, v28
	v_and_b32_e32 v3, 0xffff0000, v29
	v_lshlrev_b32_e32 v2, 16, v29
	v_pk_mul_f32 v[0:1], v[142:143], v[0:1]
	v_pk_mul_f32 v[2:3], v[142:143], v[2:3]
	v_cvt_pk_bf16_f32 v0, v0, v1
	v_cvt_pk_bf16_f32 v1, v2, v3
	v_and_b32_e32 v3, 0xffff0000, v30
	v_lshlrev_b32_e32 v2, 16, v30
	v_and_b32_e32 v5, 0xffff0000, v31
	v_lshlrev_b32_e32 v4, 16, v31
	v_pk_mul_f32 v[2:3], v[142:143], v[2:3]
	v_pk_mul_f32 v[4:5], v[142:143], v[4:5]
	v_cvt_pk_bf16_f32 v2, v2, v3
	v_cvt_pk_bf16_f32 v3, v4, v5
	ds_write_b128 v186, v[0:3]
	s_and_saveexec_b64 s[20:21], vcc
	s_cbranch_execz .LBB0_422
	ds_write_b32 v159, v200
	ds_write_b32 v158, v187
.LBB0_422:
	s_or_b64 exec, exec, s[20:21]
	s_lshl_b32 s20, s43, 6
	s_add_i32 s20, s20, s42
	s_mul_i32 s21, s20, 0x3080
	s_add_u32 s21, s30, s21
	s_addc_u32 s48, s31, 0
	v_cvt_pk_bf16_f32 v0, v64, v65
	v_cvt_pk_bf16_f32 v1, v66, v67
	v_cvt_pk_bf16_f32 v2, v60, v61
	v_cvt_pk_bf16_f32 v3, v62, v63
	s_add_u32 s44, s21, 0xc2000
	ds_write2st64_b64 v189, v[0:1], v[2:3] offset1:17
	v_cvt_pk_bf16_f32 v0, v56, v57
	v_cvt_pk_bf16_f32 v1, v58, v59
	v_cvt_pk_bf16_f32 v2, v52, v53
	v_cvt_pk_bf16_f32 v3, v54, v55
	s_addc_u32 s45, s48, 0
	ds_write2st64_b64 v189, v[0:1], v[2:3] offset0:34 offset1:51
	v_cvt_pk_bf16_f32 v0, v48, v49
	v_cvt_pk_bf16_f32 v1, v50, v51
	v_cvt_pk_bf16_f32 v2, v44, v45
	v_cvt_pk_bf16_f32 v3, v46, v47
	s_add_u32 s46, s21, 0xc2800
	ds_write2st64_b64 v190, v[0:1], v[2:3] offset1:17
	v_cvt_pk_bf16_f32 v0, v40, v41
	v_cvt_pk_bf16_f32 v1, v42, v43
	v_cvt_pk_bf16_f32 v2, v36, v37
	v_cvt_pk_bf16_f32 v3, v38, v39
	s_addc_u32 s47, s48, 0
	ds_write2st64_b64 v190, v[0:1], v[2:3] offset0:34 offset1:51
	v_lshl_add_u64 v[0:1], s[44:45], 0, v[98:99]
	v_lshl_add_u64 v[2:3], s[46:47], 0, v[98:99]
	v_lshl_add_u64 v[8:9], s[44:45], 0, v[118:119]
	v_lshl_add_u64 v[10:11], s[46:47], 0, v[118:119]
	v_lshl_add_u64 v[16:17], s[44:45], 0, v[120:121]
	v_lshl_add_u64 v[18:19], s[46:47], 0, v[120:121]
	v_lshl_add_u64 v[24:25], s[44:45], 0, v[122:123]
	v_lshl_add_u64 v[26:27], s[46:47], 0, v[122:123]
	v_lshl_add_u64 v[28:29], s[44:45], 0, v[132:133]
	v_lshl_add_u64 v[68:69], s[44:45], 0, v[124:125]
	s_waitcnt lgkmcnt(0)
	s_barrier
	global_load_dwordx4 v[4:7], v[0:1], off
	s_nop 0
	global_load_dwordx4 v[0:3], v[2:3], off
	s_nop 0
	global_load_dwordx4 v[12:15], v[8:9], off
	s_nop 0
	global_load_dwordx4 v[8:11], v[10:11], off
	s_nop 0
	global_load_dwordx4 v[20:23], v[16:17], off
	s_nop 0
	global_load_dwordx4 v[16:19], v[18:19], off
	s_nop 0
	global_load_dwordx4 v[32:35], v[24:25], off
	s_nop 0
	global_load_dwordx4 v[24:27], v[26:27], off
	v_lshl_add_u64 v[70:71], s[44:45], 0, v[126:127]
	v_lshl_add_u64 v[72:73], s[44:45], 0, v[128:129]
	global_load_dwordx4 v[28:31], v[28:29], off
	s_nop 0
	global_load_ushort v216, v[68:69], off
	global_load_ushort v215, v[70:71], off
	global_load_ushort v214, v[72:73], off
	v_lshl_add_u64 v[68:69], s[44:45], 0, v[130:131]
	s_add_u32 s44, s21, 0xc2020
	s_addc_u32 s45, s48, 0
	v_lshl_add_u64 v[70:71], s[44:45], 0, v[124:125]
	v_lshl_add_u64 v[72:73], s[44:45], 0, v[126:127]
	v_lshl_add_u64 v[74:75], s[44:45], 0, v[128:129]
	v_lshl_add_u64 v[76:77], s[44:45], 0, v[130:131]
	global_load_ushort v213, v[68:69], off
	global_load_ushort v212, v[70:71], off
	global_load_ushort v211, v[72:73], off
	global_load_ushort v210, v[74:75], off
	global_load_ushort v209, v[76:77], off
	v_add_u32_e32 v217, 0x11000, v177
	v_add_u32_e32 v242, 0x11000, v176
	ds_read_b128 v[218:221], v178
	ds_read_b128 v[222:225], v177 offset:34816
	ds_read_b128 v[226:229], v217
	ds_read_b128 v[230:233], v176 offset:34816
	ds_read_b128 v[234:237], v242
	ds_read_b128 v[238:241], v178 offset:64
	ds_read_b128 v[76:79], v177 offset:34880
	ds_read_b128 v[248:251], v217 offset:64
	s_waitcnt lgkmcnt(6)
	v_mfma_f32_16x16x32_bf16 v[84:87], v[218:221], v[222:225], 0
	ds_read_b128 v[222:225], v176 offset:34880
	s_waitcnt lgkmcnt(6)
	v_mfma_f32_16x16x32_bf16 v[72:75], v[218:221], v[226:229], 0
	ds_read_b128 v[226:229], v242 offset:64
	s_waitcnt lgkmcnt(6)
	v_mfma_f32_16x16x32_bf16 v[80:83], v[218:221], v[230:233], 0
	ds_read_b128 v[230:233], v178 offset:128
	s_waitcnt lgkmcnt(6)
	v_mfma_f32_16x16x32_bf16 v[68:71], v[218:221], v[234:237], 0
	ds_read_b128 v[234:237], v177 offset:34944
	ds_read_b128 v[218:221], v217 offset:128
	s_waitcnt lgkmcnt(6)
	v_mfma_f32_16x16x32_bf16 v[84:87], v[238:241], v[76:79], v[84:87]
	ds_read_b128 v[76:79], v176 offset:34944
	s_waitcnt lgkmcnt(6)
	v_mfma_f32_16x16x32_bf16 v[72:75], v[238:241], v[248:251], v[72:75]
	ds_read_b128 v[248:251], v242 offset:128
	s_waitcnt lgkmcnt(6)
	v_mfma_f32_16x16x32_bf16 v[80:83], v[238:241], v[222:225], v[80:83]
	ds_read_b128 v[222:225], v178 offset:192
	s_waitcnt lgkmcnt(6)
	v_mfma_f32_16x16x32_bf16 v[68:71], v[238:241], v[226:229], v[68:71]
	ds_read_b128 v[226:229], v177 offset:35008
	ds_read_b128 v[238:241], v217 offset:192
	s_waitcnt lgkmcnt(6)
	v_mfma_f32_16x16x32_bf16 v[84:87], v[230:233], v[234:237], v[84:87]
	ds_read_b128 v[234:237], v176 offset:35008
	s_waitcnt lgkmcnt(6)
	v_mfma_f32_16x16x32_bf16 v[72:75], v[230:233], v[218:221], v[72:75]
	ds_read_b128 v[218:221], v242 offset:192
	s_waitcnt lgkmcnt(6)
	v_mfma_f32_16x16x32_bf16 v[80:83], v[230:233], v[76:79], v[80:83]
	ds_read_b128 v[76:79], v178 offset:256
	s_waitcnt lgkmcnt(6)
	v_mfma_f32_16x16x32_bf16 v[68:71], v[230:233], v[248:251], v[68:71]
	ds_read_b128 v[248:251], v177 offset:35072
	ds_read_b128 v[230:233], v217 offset:256
	s_waitcnt lgkmcnt(6)
	v_mfma_f32_16x16x32_bf16 v[84:87], v[222:225], v[226:229], v[84:87]
	ds_read_b128 v[226:229], v176 offset:35072
	s_waitcnt lgkmcnt(6)
; __device__ __forceinline__ float ex2(float x) { return __builtin_amdgcn_exp2f(x); }
; template <int DK, int MODE>
; __device__ void rec_prompt_item(const Params& p, const int item, unsigned char* smem) {
;     ...
;         sc[x] = __builtin_amdgcn_mfma_f32_16x16x32_bf16(a, bk[x], sc[x], 0, 0, 0);
;         cr[x] = __builtin_amdgcn_mfma_f32_16x16x32_bf16(a, bs[x], cr[x], 0, 0, 0);
;       }
;     }
;     float ci[4];
; #pragma unroll
;     for (int r = 0; r < 4; ++r) ci[r] = cumS[16 * fi + 4 * g + r];
; #pragma unroll
;     for (int x = 0; x < 2; ++x) {
;       const int fj = fe0 + x;
;       const int j = 16 * fj + l15;
;       const float cj = cumS[j], uj = uS[j];
; #pragma unroll
;       for (int r = 0; r < 4; ++r) {
;         const int i = 16 * fi + 4 * g + r;
;         float v = 0.f;
;         if (j <= i) v = sc[x][r] * ex2(ci[r] - cj) * uj;
;         *(u16*)(Ps + i * PS + j * 2) = f2bf(v);
;       }
;     }
;     {
;       const float atot = ex2(cumS[63]);
; #pragma unroll
;       for (int mf = 0; mf < MF; ++mf)
; #pragma unroll
;         for (int nf = 0; nf < 4; ++nf)
; #pragma unroll
;           for (int r = 0; r < 4; ++r) S[mf][nf][r] *= atot;
; #pragma unroll
;       for (int ks = 0; ks < 2; ++ks) {
;         bf16x8 af[MF], bfv[4];
; #pragma unroll
;         for (int mf = 0; mf < MF; ++mf) af[mf] = trfrag(Ks, QS, 32 * ks, dw + 16 * mf, lane);
; #pragma unroll
;         for (int nf = 0; nf < 4; ++nf) bfv[nf] = trfrag(Vts, VS, 32 * ks, 16 * nf, lane);
; #pragma unroll
;         for (int mf = 0; mf < MF; ++mf)
; #pragma unroll
;           for (int nf = 0; nf < 4; ++nf)
;             S[mf][nf] = __builtin_amdgcn_mfma_f32_16x16x32_bf16(af[mf], bfv[nf], S[mf][nf], 0, 0, 0);
;       }
;     }
;     __syncthreads();
	v_mfma_f32_16x16x32_bf16 v[72:75], v[222:225], v[238:241], v[72:75]
	ds_read_b128 v[238:241], v242 offset:256
	s_waitcnt lgkmcnt(6)
	v_mfma_f32_16x16x32_bf16 v[80:83], v[222:225], v[234:237], v[80:83]
	ds_read_b128 v[234:237], v178 offset:320
	s_waitcnt lgkmcnt(6)
	v_mfma_f32_16x16x32_bf16 v[68:71], v[222:225], v[218:221], v[68:71]
	ds_read_b128 v[218:221], v177 offset:35136
	ds_read_b128 v[222:225], v217 offset:320
	s_waitcnt lgkmcnt(6)
	v_mfma_f32_16x16x32_bf16 v[84:87], v[76:79], v[248:251], v[84:87]
	ds_read_b128 v[248:251], v176 offset:35136
	s_waitcnt lgkmcnt(6)
	v_mfma_f32_16x16x32_bf16 v[72:75], v[76:79], v[230:233], v[72:75]
	ds_read_b128 v[230:233], v242 offset:320
	s_waitcnt lgkmcnt(6)
	v_mfma_f32_16x16x32_bf16 v[80:83], v[76:79], v[226:229], v[80:83]
	ds_read_b128 v[226:229], v178 offset:384
	s_waitcnt lgkmcnt(6)
	v_mfma_f32_16x16x32_bf16 v[68:71], v[76:79], v[238:241], v[68:71]
	ds_read_b128 v[238:241], v177 offset:35200
	ds_read_b128 v[76:79], v217 offset:384
	s_waitcnt lgkmcnt(6)
	v_mfma_f32_16x16x32_bf16 v[84:87], v[234:237], v[218:221], v[84:87]
	ds_read_b128 v[218:221], v176 offset:35200
	s_waitcnt lgkmcnt(6)
	v_mfma_f32_16x16x32_bf16 v[72:75], v[234:237], v[222:225], v[72:75]
	ds_read_b128 v[222:225], v242 offset:384
	s_waitcnt lgkmcnt(6)
	v_mfma_f32_16x16x32_bf16 v[80:83], v[234:237], v[248:251], v[80:83]
	ds_read_b128 v[248:251], v178 offset:448
	s_waitcnt lgkmcnt(6)
	v_mfma_f32_16x16x32_bf16 v[68:71], v[234:237], v[230:233], v[68:71]
	ds_read_b128 v[230:233], v177 offset:35264
	ds_read_b128 v[234:237], v217 offset:448
	s_waitcnt lgkmcnt(6)
	v_mfma_f32_16x16x32_bf16 v[84:87], v[226:229], v[238:241], v[84:87]
	ds_read_b128 v[238:241], v176 offset:35264
	s_waitcnt lgkmcnt(6)
	v_mfma_f32_16x16x32_bf16 v[72:75], v[226:229], v[76:79], v[72:75]
	ds_read_b128 v[76:79], v242 offset:448
	s_waitcnt lgkmcnt(6)
	v_mfma_f32_16x16x32_bf16 v[80:83], v[226:229], v[218:221], v[80:83]
	s_waitcnt lgkmcnt(5)
	v_mfma_f32_16x16x32_bf16 v[68:71], v[226:229], v[222:225], v[68:71]
	s_waitcnt lgkmcnt(3)
	v_mfma_f32_16x16x32_bf16 v[84:87], v[248:251], v[230:233], v[84:87]
	s_waitcnt lgkmcnt(2)
	v_mfma_f32_16x16x32_bf16 v[72:75], v[248:251], v[234:237], v[72:75]
	s_waitcnt lgkmcnt(1)
	v_mfma_f32_16x16x32_bf16 v[80:83], v[248:251], v[238:241], v[80:83]
	s_waitcnt lgkmcnt(0)
	v_mfma_f32_16x16x32_bf16 v[68:71], v[248:251], v[76:79], v[68:71]
	s_movk_i32 s21, 0x200
	s_cmpk_eq_i32 s21, 0x200
	ds_read_b128 v[76:79], v191
	ds_read_b32 v194, v167
	ds_read_b32 v217, v168
	ds_read_b32 v218, v169
	ds_read_b32 v219, v170
	ds_read_b32 v220, v188
	s_waitcnt lgkmcnt(4)
	v_sub_f32_e32 v221, v76, v194
	v_exp_f32_e32 v221, v221
	v_sub_f32_e32 v222, v77, v194
	v_exp_f32_e32 v222, v222
	s_lshl_b32 s21, s20, 12
	v_mul_f32_e32 v84, v84, v221
	s_waitcnt lgkmcnt(3)
	v_mul_f32_e32 v84, v217, v84
	v_cvt_pk_bf16_f32 v84, v84, s0
	v_cndmask_b32_e64 v84, v84, 0, s[4:5]
	ds_write_b16 v192, v84
	v_mul_f32_e32 v84, v85, v222
	v_sub_f32_e32 v85, v78, v194
	v_exp_f32_e32 v85, v85
	v_mul_f32_e32 v84, v217, v84
	v_cvt_pk_bf16_f32 v84, v84, s0
	v_cndmask_b32_e64 v84, v84, 0, s[6:7]
	ds_write_b16 v192, v84 offset:144
	v_mul_f32_e32 v84, v86, v85
	v_sub_f32_e32 v85, v79, v194
	v_exp_f32_e32 v85, v85
	v_mul_f32_e32 v84, v217, v84
	v_cvt_pk_bf16_f32 v84, v84, s0
	v_cndmask_b32_e64 v84, v84, 0, s[8:9]
	ds_write_b16 v192, v84 offset:288
	v_mul_f32_e32 v84, v87, v85
	s_waitcnt lgkmcnt(5)
	v_sub_f32_e32 v85, v76, v218
	v_mul_f32_e32 v84, v217, v84
	v_exp_f32_e32 v85, v85
	v_cvt_pk_bf16_f32 v84, v84, s0
	v_cndmask_b32_e64 v84, v84, 0, s[10:11]
	ds_write_b16 v192, v84 offset:432
	v_sub_f32_e32 v84, v77, v218
	v_mul_f32_e32 v80, v80, v85
	v_exp_f32_e32 v84, v84
	s_waitcnt lgkmcnt(5)
	v_mul_f32_e32 v80, v219, v80
	v_cvt_pk_bf16_f32 v80, v80, s0
	v_cndmask_b32_e64 v80, v80, 0, s[12:13]
	ds_write_b16 v193, v80
	v_mul_f32_e32 v80, v81, v84
	v_sub_f32_e32 v81, v78, v218
	v_exp_f32_e32 v81, v81
	v_mul_f32_e32 v80, v219, v80
	v_cvt_pk_bf16_f32 v80, v80, s0
	v_cndmask_b32_e64 v80, v80, 0, s[14:15]
	ds_write_b16 v193, v80 offset:144
	v_mul_f32_e32 v80, v82, v81
	v_sub_f32_e32 v81, v79, v218
	v_exp_f32_e32 v81, v81
	v_mul_f32_e32 v80, v219, v80
	v_cvt_pk_bf16_f32 v80, v80, s0
	v_cndmask_b32_e64 v80, v80, 0, s[16:17]
	ds_write_b16 v193, v80 offset:288
	v_mul_f32_e32 v80, v83, v81
	v_mul_f32_e32 v80, v219, v80
	v_cvt_pk_bf16_f32 v80, v80, s0
	v_cndmask_b32_e64 v80, v80, 0, s[18:19]
	ds_write_b16 v193, v80 offset:432
	s_waitcnt lgkmcnt(8)
	v_exp_f32_e32 v194, v220
	ds_read_b64_tr_b16 v[82:83], v195 offset:36992
	ds_read_b64_tr_b16 v[80:81], v195 offset:34816
	ds_read_b64_tr_b16 v[86:87], v195 offset:37024
	ds_read_b64_tr_b16 v[84:85], v195 offset:34848
	ds_read_b64_tr_b16 v[220:221], v196 offset:640
	ds_read_b64_tr_b16 v[218:219], v196
	ds_read_b64_tr_b16 v[222:223], v196 offset:32
	ds_read_b64_tr_b16 v[226:227], v196 offset:64
	ds_read_b64_tr_b16 v[230:231], v196 offset:96
	ds_read_b64_tr_b16 v[224:225], v196 offset:672
	ds_read_b64_tr_b16 v[228:229], v196 offset:704
	ds_read_b64_tr_b16 v[232:233], v196 offset:736
	v_add_u32_e32 v217, v163, v164
	s_add_u32 s44, s33, s21
	v_pk_mul_f32 v[66:67], v[66:67], v[194:195] op_sel_hi:[1,0]
	v_pk_mul_f32 v[64:65], v[64:65], v[194:195] op_sel_hi:[1,0]
	v_pk_mul_f32 v[62:63], v[62:63], v[194:195] op_sel_hi:[1,0]
	v_pk_mul_f32 v[60:61], v[60:61], v[194:195] op_sel_hi:[1,0]
	v_pk_mul_f32 v[58:59], v[58:59], v[194:195] op_sel_hi:[1,0]
	v_pk_mul_f32 v[56:57], v[56:57], v[194:195] op_sel_hi:[1,0]
	v_pk_mul_f32 v[54:55], v[54:55], v[194:195] op_sel_hi:[1,0]
	v_pk_mul_f32 v[52:53], v[52:53], v[194:195] op_sel_hi:[1,0]
	v_pk_mul_f32 v[50:51], v[50:51], v[194:195] op_sel_hi:[1,0]
	v_pk_mul_f32 v[48:49], v[48:49], v[194:195] op_sel_hi:[1,0]
	v_pk_mul_f32 v[46:47], v[46:47], v[194:195] op_sel_hi:[1,0]
	v_pk_mul_f32 v[44:45], v[44:45], v[194:195] op_sel_hi:[1,0]
	v_pk_mul_f32 v[42:43], v[42:43], v[194:195] op_sel_hi:[1,0]
	v_pk_mul_f32 v[40:41], v[40:41], v[194:195] op_sel_hi:[1,0]
	v_pk_mul_f32 v[38:39], v[38:39], v[194:195] op_sel_hi:[1,0]
	v_pk_mul_f32 v[36:37], v[36:37], v[194:195] op_sel_hi:[1,0]
	s_waitcnt lgkmcnt(6)
; template <int DK, int MODE>
; __device__ void rec_prompt_item(const Params& p, const int item, unsigned char* smem) {
;     ...
;         for (int mf = 0; mf < MF; ++mf) af[mf] = trfrag(Ks, QS, 32 * ks, dw + 16 * mf, lane);
; #pragma unroll
;         for (int nf = 0; nf < 4; ++nf) bfv[nf] = trfrag(Vts, VS, 32 * ks, 16 * nf, lane);
; #pragma unroll
;         for (int mf = 0; mf < MF; ++mf)
; #pragma unroll
;           for (int nf = 0; nf < 4; ++nf)
;             S[mf][nf] = __builtin_amdgcn_mfma_f32_16x16x32_bf16(af[mf], bfv[nf], S[mf][nf], 0, 0, 0);
;       }
;     }
;     __syncthreads();
;     f32x4 in[2];
; #pragma unroll
;     for (int x = 0; x < 2; ++x) in[x] = (f32x4){0.f, 0.f, 0.f, 0.f};
; #pragma unroll
;     for (int ks = 0; ks < 2; ++ks) {
;       const bf16x8 a = *(const bf16x8*)(Ps + (16 * fi + l15) * PS + ks * 64 + g * 16);
;       bf16x8 bv[2];
; #pragma unroll
;       for (int x = 0; x < 2; ++x) bv[x] = trfrag(Vs, VS, 32 * ks, 16 * (fe0 + x), lane);
; #pragma unroll
;       for (int x = 0; x < 2; ++x) in[x] = __builtin_amdgcn_mfma_f32_16x16x32_bf16(a, bv[x], in[x], 0, 0, 0);
;     }
;     {
;       float ss[4] = {0.f, 0.f, 0.f, 0.f};
;       u16* aout = (u16*)(p.ws + OFF_A2);
;       float* parts = (float*)(p.ws + OFF_PARTS);
; #pragma unroll
;       for (int x = 0; x < 2; ++x) {
;         const int e = 16 * (fe0 + x) + l15;
;         const float gn = gnv[x];
;         const int ocol = (MODE == 0) ? (h * 512 + s * 64 + e) : (h * 64 + e);
; #pragma unroll
;         for (int r = 0; r < 4; ++r) {
;           const int i = 16 * fi + 4 * g + r;
;           float o = in[x][r] + cr[x][r] * ex2(ci[r]);
;           const float gv = bf2f(gzc[x][r]);
;           float val;
;           if (MODE == 0) {
;             ss[r] += o * o;
;             val = o * gn * silu(gv);
;           } else {
;             const float xs = bf2f(*(const u16*)(Vs + i * VS + e * 2));
;             const float y = o + xs * dsk;
;             const float gg = y * silu(gv);
;             ss[r] += gg * gg;
;             val = gg * gn;
;           }
;           *(u16*)((char*)aout + (size_t)r0 * 4096 + 32 * x + aoff[r]) = f2bf(val);
;         }
;       }
; #pragma unroll
;       for (int r = 0; r < 4; ++r) {
;         const float v = row16_sum(ss[r]);
;         if (l15 == 0) {
;           const int i = 16 * fi + 4 * g + r;
	v_mfma_f32_16x16x32_bf16 v[64:67], v[80:83], v[218:221], v[64:67]
	s_waitcnt vmcnt(24)
	v_lshlrev_b32_e32 v194, 16, v208
	v_mul_f32_e32 v208, 0xbfb8aa3b, v194
	v_exp_f32_e32 v208, v208
	s_waitcnt lgkmcnt(2)
	v_mfma_f32_16x16x32_bf16 v[60:63], v[80:83], v[222:225], v[60:63]
	s_addc_u32 s45, s34, 0
	s_waitcnt lgkmcnt(1)
	v_mfma_f32_16x16x32_bf16 v[56:59], v[80:83], v[226:229], v[56:59]
	s_waitcnt lgkmcnt(0)
	v_mfma_f32_16x16x32_bf16 v[52:55], v[80:83], v[230:233], v[52:55]
	v_mfma_f32_16x16x32_bf16 v[48:51], v[84:87], v[218:221], v[48:51]
	v_mfma_f32_16x16x32_bf16 v[44:47], v[84:87], v[222:225], v[44:47]
	v_mfma_f32_16x16x32_bf16 v[80:83], v[84:87], v[226:229], v[40:43]
	v_mfma_f32_16x16x32_bf16 v[84:87], v[84:87], v[230:233], v[36:39]
	s_nop 2
	ds_read_b64_tr_b16 v[38:39], v197 offset:36992
	ds_read_b64_tr_b16 v[36:37], v197 offset:34816
	ds_read_b64_tr_b16 v[220:221], v197 offset:37024
	ds_read_b64_tr_b16 v[218:219], v197 offset:34848
	ds_read_b64_tr_b16 v[42:43], v196 offset:5760
	ds_read_b64_tr_b16 v[40:41], v196 offset:5120
	ds_read_b64_tr_b16 v[222:223], v196 offset:5152
	ds_read_b64_tr_b16 v[226:227], v196 offset:5184
	ds_read_b64_tr_b16 v[230:231], v196 offset:5216
	ds_read_b64_tr_b16 v[224:225], v196 offset:5792
	ds_read_b64_tr_b16 v[228:229], v196 offset:5824
	ds_read_b64_tr_b16 v[232:233], v196 offset:5856
	s_waitcnt lgkmcnt(0)
	s_barrier
	v_mfma_f32_16x16x32_bf16 v[64:67], v[36:39], v[40:43], v[64:67]
	v_mfma_f32_16x16x32_bf16 v[60:63], v[36:39], v[222:225], v[60:63]
	v_mfma_f32_16x16x32_bf16 v[56:59], v[36:39], v[226:229], v[56:59]
	v_mfma_f32_16x16x32_bf16 v[52:55], v[36:39], v[230:233], v[52:55]
	v_mfma_f32_16x16x32_bf16 v[36:39], v[218:221], v[226:229], v[80:83]
	s_nop 2
	ds_read_b128 v[80:83], v198
	v_mfma_f32_16x16x32_bf16 v[48:51], v[218:221], v[40:43], v[48:51]
	v_mfma_f32_16x16x32_bf16 v[40:43], v[218:221], v[222:225], v[44:47]
	v_mfma_f32_16x16x32_bf16 v[44:47], v[218:221], v[230:233], v[84:87]
	s_nop 2
	ds_read_b64_tr_b16 v[84:85], v217
	ds_read_b64_tr_b16 v[86:87], v217 offset:640
	v_add_u32_e32 v218, v163, v165
	v_add_u32_e32 v219, v166, v164
	ds_read_b64_tr_b16 v[220:221], v218
	ds_read_b64_tr_b16 v[222:223], v218 offset:640
	ds_read_b128 v[224:227], v198 offset:64
	ds_read_b64_tr_b16 v[228:229], v219
	ds_read_b64_tr_b16 v[230:231], v219 offset:640
	s_waitcnt lgkmcnt(5)
	v_mfma_f32_16x16x32_bf16 v[84:87], v[80:83], v[84:87], 0
	s_waitcnt lgkmcnt(3)
	v_mfma_f32_16x16x32_bf16 v[232:235], v[80:83], v[220:223], 0
	v_exp_f32_e32 v221, v76
	v_add_f32_e32 v76, 1.0, v208
	v_rcp_f32_e32 v76, v76
	s_waitcnt lgkmcnt(0)
	v_mfma_f32_16x16x32_bf16 v[80:83], v[224:227], v[228:231], v[84:87]
	v_add_u32_e32 v220, v166, v165
	v_lshl_add_u64 v[222:223], s[44:45], 0, v[134:135]
	v_mul_f32_e32 v76, v76, v194
	v_exp_f32_e32 v194, v77
	ds_read_b64_tr_b16 v[236:237], v220
	ds_read_b64_tr_b16 v[238:239], v220 offset:640
	s_nop 1
	v_fma_f32 v208, v72, v221, v80
	v_mul_f32_e32 v72, v117, v208
	v_mul_f32_e32 v72, v76, v72
	s_waitcnt vmcnt(23)
	v_lshlrev_b32_e32 v76, 16, v207
	v_mul_f32_e32 v80, 0xbfb8aa3b, v76
	v_exp_f32_e32 v80, v80
	v_cvt_pk_bf16_f32 v72, v72, s0
	v_fma_f32 v73, v73, v194, v81
	global_store_short v[222:223], v72, off
	v_add_f32_e32 v77, 1.0, v80
	v_rcp_f32_e32 v77, v77
	v_mul_f32_e32 v72, v117, v73
	s_waitcnt vmcnt(23)
	v_lshlrev_b32_e32 v80, 16, v206
	v_exp_f32_e32 v206, v78
	v_mul_f32_e32 v76, v77, v76
	v_mul_f32_e32 v72, v76, v72
	v_mul_f32_e32 v76, 0xbfb8aa3b, v80
	v_exp_f32_e32 v81, v76
	v_cvt_pk_bf16_f32 v72, v72, s0
	v_lshl_add_u64 v[76:77], s[44:45], 0, v[136:137]
	global_store_short v[76:77], v72, off
	v_add_f32_e32 v78, 1.0, v81
	v_rcp_f32_e32 v78, v78
	v_fma_f32 v72, v74, v206, v82
	v_mul_f32_e32 v74, v117, v72
	s_waitcnt lgkmcnt(0)
	v_mfma_f32_16x16x32_bf16 v[84:87], v[224:227], v[236:239], v[232:235]
	s_waitcnt vmcnt(15)
	ds_write_b128 v181, v[4:7]
	ds_write_b128 v181, v[0:3] offset:34816
	s_waitcnt vmcnt(13)
	ds_write_b128 v182, v[12:15]
	ds_write_b128 v182, v[8:11] offset:34816
	s_waitcnt vmcnt(11)
	ds_write_b128 v183, v[20:23]
	ds_write_b128 v183, v[16:19] offset:34816
	s_waitcnt vmcnt(9)
	ds_write_b128 v184, v[32:35]
	ds_write_b128 v184, v[24:27] offset:34816
	v_mul_f32_e32 v78, v78, v80
	v_mul_f32_e32 v74, v78, v74
	s_waitcnt vmcnt(23)
	v_lshlrev_b32_e32 v78, 16, v205
	v_mul_f32_e32 v80, 0xbfb8aa3b, v78
	v_exp_f32_e32 v82, v80
	v_exp_f32_e32 v205, v79
	v_cvt_pk_bf16_f32 v74, v74, s0
	v_lshl_add_u64 v[80:81], s[44:45], 0, v[138:139]
	v_add_f32_e32 v79, 1.0, v82
	v_rcp_f32_e32 v79, v79
	v_fmac_f32_e32 v83, v75, v205
	global_store_short v[80:81], v74, off
	v_mul_f32_e32 v74, v117, v83
	v_mul_f32_e32 v75, v79, v78
	v_mul_f32_e32 v74, v75, v74
	v_cvt_pk_bf16_f32 v74, v74, s0
	v_lshl_add_u64 v[78:79], s[44:45], 0, v[140:141]
	global_store_short v[78:79], v74, off
	s_waitcnt vmcnt(24)
	v_lshlrev_b32_e32 v74, 16, v204
	v_mul_f32_e32 v75, 0xbfb8aa3b, v74
	v_exp_f32_e32 v75, v75
	v_fma_f32 v68, v68, v221, v84
	s_waitcnt vmcnt(23)
	v_lshlrev_b32_e32 v84, 16, v203
	v_mul_f32_e32 v203, 0xbfb8aa3b, v84
	v_add_f32_e32 v75, 1.0, v75
	v_rcp_f32_e32 v75, v75
	v_exp_f32_e32 v203, v203
	v_mul_f32_e32 v82, v68, v68
	v_mul_f32_e32 v68, v199, v68
	v_mul_f32_e32 v74, v75, v74
	v_mul_f32_e32 v68, v74, v68
	v_add_f32_e32 v74, 1.0, v203
	v_rcp_f32_e32 v75, v74
	v_cvt_pk_bf16_f32 v68, v68, s0
	v_fma_f32 v74, v69, v194, v85
	global_store_short v[222:223], v68, off offset:32
	v_mul_f32_e32 v68, v199, v74
	v_mul_f32_e32 v69, v75, v84
	v_mul_f32_e32 v68, v69, v68
	s_waitcnt vmcnt(23)
	v_lshlrev_b32_e32 v69, 16, v202
	v_mul_f32_e32 v75, 0xbfb8aa3b, v69
	v_exp_f32_e32 v75, v75
	v_cvt_pk_bf16_f32 v68, v68, s0
	global_store_short v[76:77], v68, off offset:32
	s_waitcnt vmcnt(23)
	v_lshlrev_b32_e32 v76, 16, v201
	v_add_f32_e32 v75, 1.0, v75
	v_rcp_f32_e32 v75, v75
	v_mul_f32_e32 v77, 0xbfb8aa3b, v76
	v_exp_f32_e32 v77, v77
	v_fma_f32 v70, v70, v206, v86
	v_mul_f32_e32 v68, v199, v70
	v_mul_f32_e32 v69, v75, v69
	v_mul_f32_e32 v68, v69, v68
	v_add_f32_e32 v69, 1.0, v77
	v_rcp_f32_e32 v69, v69
	v_cvt_pk_bf16_f32 v68, v68, s0
	v_fmac_f32_e32 v87, v71, v205
	v_fmac_f32_e32 v82, v208, v208
	global_store_short v[80:81], v68, off offset:32
	v_mul_f32_e32 v68, v199, v87
	v_mul_f32_e32 v69, v69, v76
	v_mul_f32_e32 v68, v69, v68
	v_cvt_pk_bf16_f32 v68, v68, s0
	v_add_f32_dpp v69, v82, v82 quad_perm:[1,0,3,2] row_mask:0xf bank_mask:0xf bound_ctrl:1
	global_store_short v[78:79], v68, off offset:32
	v_add_u32_e32 v68, s20, v91
	v_add_f32_dpp v69, v69, v69 quad_perm:[2,3,0,1] row_mask:0xf bank_mask:0xf bound_ctrl:1
	s_nop 1
	v_add_f32_dpp v71, v69, v69 row_ror:4 row_mask:0xf bank_mask:0xf bound_ctrl:1
	s_nop 1
	v_mov_b32_dpp v75, v71 row_ror:8 row_mask:0xf bank_mask:0xf bound_ctrl:1
	s_and_saveexec_b64 s[20:21], s[2:3]
	s_cbranch_execz .LBB0_426
	v_ashrrev_i32_e32 v69, 31, v68
	v_lshlrev_b64 v[76:77], 8, v[68:69]
	v_lshl_add_u64 v[76:77], v[144:145], 0, v[76:77]
	v_add_f32_e32 v69, v71, v75
	global_store_dword v[76:77], v69, off

; __device__ __forceinline__ float bf2f(u16 h) { return __uint_as_float(((uint32_t)h) << 16); }
; __device__ __forceinline__ float ex2(float x) { return __builtin_amdgcn_exp2f(x); }
; template <int DK, int MODE>
; __device__ void rec_prompt_item(const Params& p, const int item, unsigned char* smem) {
;     ...
;     {
;       const u32x4 rvv = rv[par];
;       *(u32x4*)(Vs + vrow * VS + vkc * 16) = rvv;
;       float cj, uj, cl;
;       if (MODE == 0) { cj = (float)(vrow + 1) * lg; uj = 1.f; cl = 64.f * lg; } else { cj = pcj[par]; uj = puj[par]; cl = pclast[par]; }
;       const float wj = uj * ex2(cl - cj);
;       u32x4 o;
;       o.x = pack2(bf2f((u16)(rvv.x & 0xffff)) * wj, bf2f((u16)(rvv.x >> 16)) * wj);
;       o.y = pack2(bf2f((u16)(rvv.y & 0xffff)) * wj, bf2f((u16)(rvv.y >> 16)) * wj);
;       o.z = pack2(bf2f((u16)(rvv.z & 0xffff)) * wj, bf2f((u16)(rvv.z >> 16)) * wj);
;       o.w = pack2(bf2f((u16)(rvv.w & 0xffff)) * wj, bf2f((u16)(rvv.w >> 16)) * wj);
;       *(u32x4*)(Vts + vrow * VS + vkc * 16) = o;
;     }
;     if (tid < 64) {
;       if (MODE == 0) { cumS[tid] = (float)(tid + 1) * lg; uS[tid] = 1.f; } else { cumS[tid] = pct[par]; uS[tid] = put[par]; }
;     }
;     ...
;     __syncthreads();
.LBB0_432:
	s_or_b64 exec, exec, s[20:21]
	s_waitcnt vmcnt(16)
	v_and_b32_e32 v69, 0xffff0000, v28
	v_lshlrev_b32_e32 v68, 16, v28
	v_and_b32_e32 v71, 0xffff0000, v29
	v_lshlrev_b32_e32 v70, 16, v29
	v_pk_mul_f32 v[68:69], v[142:143], v[68:69]
	v_pk_mul_f32 v[70:71], v[142:143], v[70:71]
	v_cvt_pk_bf16_f32 v68, v68, v69
	v_cvt_pk_bf16_f32 v69, v70, v71
	v_and_b32_e32 v71, 0xffff0000, v30
	v_lshlrev_b32_e32 v70, 16, v30
	v_and_b32_e32 v73, 0xffff0000, v31
	v_lshlrev_b32_e32 v72, 16, v31
	v_pk_mul_f32 v[70:71], v[142:143], v[70:71]
	v_pk_mul_f32 v[72:73], v[142:143], v[72:73]
	v_cvt_pk_bf16_f32 v70, v70, v71
	v_cvt_pk_bf16_f32 v71, v72, v73
	s_barrier
	ds_write_b128 v185, v[28:31]
	ds_write_b128 v186, v[68:71]
	s_and_saveexec_b64 s[20:21], vcc
	s_cbranch_execz .LBB0_434
	ds_write_b32 v159, v200
	ds_write_b32 v158, v187

; __device__ __forceinline__ float ex2(float x) { return __builtin_amdgcn_exp2f(x); }
; template <int DK, int MODE>
; __device__ void rec_prompt_item(const Params& p, const int item, unsigned char* smem) {
;     ...
;     f32x4 sc[2], cr[2];
; #pragma unroll
;     for (int x = 0; x < 2; ++x) { sc[x] = (f32x4){0.f, 0.f, 0.f, 0.f}; cr[x] = (f32x4){0.f, 0.f, 0.f, 0.f}; }
; #pragma unroll KUNR
;     for (int ks = 0; ks < KS; ++ks) {
;       const bf16x8 a = *(const bf16x8*)(Qs + (16 * fi + l15) * QS + ks * 64 + g * 16);
;       bf16x8 bk[2], bs[2];
; #pragma unroll
;       for (int x = 0; x < 2; ++x) {
;         bk[x] = *(const bf16x8*)(Ks + (16 * (fe0 + x) + l15) * QS + ks * 64 + g * 16);
;         bs[x] = *(const bf16x8*)(STs + (16 * (fe0 + x) + l15) * QS + ks * 64 + g * 16);
;       }
; #pragma unroll
;       for (int x = 0; x < 2; ++x) {
;         sc[x] = __builtin_amdgcn_mfma_f32_16x16x32_bf16(a, bk[x], sc[x], 0, 0, 0);
;         cr[x] = __builtin_amdgcn_mfma_f32_16x16x32_bf16(a, bs[x], cr[x], 0, 0, 0);
;       }
;     }
;     float ci[4];
; #pragma unroll
;     for (int r = 0; r < 4; ++r) ci[r] = cumS[16 * fi + 4 * g + r];
; #pragma unroll
;     for (int x = 0; x < 2; ++x) {
;       const int fj = fe0 + x;
;       const int j = 16 * fj + l15;
;       const float cj = cumS[j], uj = uS[j];
; #pragma unroll
;       for (int r = 0; r < 4; ++r) {
;         const int i = 16 * fi + 4 * g + r;
;         float v = 0.f;
;         if (j <= i) v = sc[x][r] * ex2(ci[r] - cj) * uj;
;         *(u16*)(Ps + i * PS + j * 2) = f2bf(v);
;       }
;     }
.LBB0_436:
	v_add_u32_e32 v221, 0x11000, v177
	v_add_u32_e32 v246, 0x11000, v176
	ds_read_b128 v[222:225], v178
	ds_read_b128 v[226:229], v177 offset:34816
	ds_read_b128 v[230:233], v221
	ds_read_b128 v[234:237], v176 offset:34816
	ds_read_b128 v[238:241], v246
	ds_read_b128 v[242:245], v178 offset:64
	ds_read_b128 v[76:79], v177 offset:34880
	ds_read_b128 v[248:251], v221 offset:64
	s_waitcnt lgkmcnt(6)
	v_mfma_f32_16x16x32_bf16 v[84:87], v[222:225], v[226:229], 0
	ds_read_b128 v[226:229], v176 offset:34880
	s_waitcnt lgkmcnt(6)
	v_mfma_f32_16x16x32_bf16 v[72:75], v[222:225], v[230:233], 0
	ds_read_b128 v[230:233], v246 offset:64
	s_waitcnt lgkmcnt(6)
	v_mfma_f32_16x16x32_bf16 v[80:83], v[222:225], v[234:237], 0
	ds_read_b128 v[234:237], v178 offset:128
	s_waitcnt lgkmcnt(6)
	v_mfma_f32_16x16x32_bf16 v[68:71], v[222:225], v[238:241], 0
	ds_read_b128 v[238:241], v177 offset:34944
	ds_read_b128 v[222:225], v221 offset:128
	s_waitcnt lgkmcnt(6)
	v_mfma_f32_16x16x32_bf16 v[84:87], v[242:245], v[76:79], v[84:87]
	ds_read_b128 v[76:79], v176 offset:34944
	s_waitcnt lgkmcnt(6)
	v_mfma_f32_16x16x32_bf16 v[72:75], v[242:245], v[248:251], v[72:75]
	ds_read_b128 v[248:251], v246 offset:128
	s_waitcnt lgkmcnt(6)
	v_mfma_f32_16x16x32_bf16 v[80:83], v[242:245], v[226:229], v[80:83]
	ds_read_b128 v[226:229], v178 offset:192
	s_waitcnt lgkmcnt(6)
	v_mfma_f32_16x16x32_bf16 v[68:71], v[242:245], v[230:233], v[68:71]
	ds_read_b128 v[230:233], v177 offset:35008
	ds_read_b128 v[242:245], v221 offset:192
	s_waitcnt lgkmcnt(6)
	v_mfma_f32_16x16x32_bf16 v[84:87], v[234:237], v[238:241], v[84:87]
	ds_read_b128 v[238:241], v176 offset:35008
	s_waitcnt lgkmcnt(6)
	v_mfma_f32_16x16x32_bf16 v[72:75], v[234:237], v[222:225], v[72:75]
	ds_read_b128 v[222:225], v246 offset:192
	s_waitcnt lgkmcnt(6)
	v_mfma_f32_16x16x32_bf16 v[80:83], v[234:237], v[76:79], v[80:83]
	ds_read_b128 v[76:79], v178 offset:256
	s_waitcnt lgkmcnt(6)
	v_mfma_f32_16x16x32_bf16 v[68:71], v[234:237], v[248:251], v[68:71]
	ds_read_b128 v[248:251], v177 offset:35072
	ds_read_b128 v[234:237], v221 offset:256
	s_waitcnt lgkmcnt(6)
	v_mfma_f32_16x16x32_bf16 v[84:87], v[226:229], v[230:233], v[84:87]
	ds_read_b128 v[230:233], v176 offset:35072
	s_waitcnt lgkmcnt(6)
	v_mfma_f32_16x16x32_bf16 v[72:75], v[226:229], v[242:245], v[72:75]
	ds_read_b128 v[242:245], v246 offset:256
	s_waitcnt lgkmcnt(6)
	v_mfma_f32_16x16x32_bf16 v[80:83], v[226:229], v[238:241], v[80:83]
	ds_read_b128 v[238:241], v178 offset:320
	s_waitcnt lgkmcnt(6)
	v_mfma_f32_16x16x32_bf16 v[68:71], v[226:229], v[222:225], v[68:71]
	ds_read_b128 v[222:225], v177 offset:35136
	ds_read_b128 v[226:229], v221 offset:320
	s_waitcnt lgkmcnt(6)
	v_mfma_f32_16x16x32_bf16 v[84:87], v[76:79], v[248:251], v[84:87]
	ds_read_b128 v[248:251], v176 offset:35136
	s_waitcnt lgkmcnt(6)
	v_mfma_f32_16x16x32_bf16 v[72:75], v[76:79], v[234:237], v[72:75]
	ds_read_b128 v[234:237], v246 offset:320
	s_waitcnt lgkmcnt(6)
	v_mfma_f32_16x16x32_bf16 v[80:83], v[76:79], v[230:233], v[80:83]
	ds_read_b128 v[230:233], v178 offset:384
	s_waitcnt lgkmcnt(6)
	v_mfma_f32_16x16x32_bf16 v[68:71], v[76:79], v[242:245], v[68:71]
	ds_read_b128 v[242:245], v177 offset:35200
	ds_read_b128 v[76:79], v221 offset:384
	s_waitcnt lgkmcnt(6)
	v_mfma_f32_16x16x32_bf16 v[84:87], v[238:241], v[222:225], v[84:87]
	ds_read_b128 v[222:225], v176 offset:35200
	s_waitcnt lgkmcnt(6)
	v_mfma_f32_16x16x32_bf16 v[72:75], v[238:241], v[226:229], v[72:75]
	ds_read_b128 v[226:229], v246 offset:384
	s_waitcnt lgkmcnt(6)
	v_mfma_f32_16x16x32_bf16 v[80:83], v[238:241], v[248:251], v[80:83]
	ds_read_b128 v[248:251], v178 offset:448
	s_waitcnt lgkmcnt(6)
	v_mfma_f32_16x16x32_bf16 v[68:71], v[238:241], v[234:237], v[68:71]
	ds_read_b128 v[234:237], v177 offset:35264
	ds_read_b128 v[238:241], v221 offset:448
	s_waitcnt lgkmcnt(6)
	v_mfma_f32_16x16x32_bf16 v[84:87], v[230:233], v[242:245], v[84:87]
	ds_read_b128 v[242:245], v176 offset:35264
	s_waitcnt lgkmcnt(6)
	v_mfma_f32_16x16x32_bf16 v[72:75], v[230:233], v[76:79], v[72:75]
	ds_read_b128 v[76:79], v246 offset:448
	s_waitcnt lgkmcnt(6)
	v_mfma_f32_16x16x32_bf16 v[80:83], v[230:233], v[222:225], v[80:83]
	s_waitcnt lgkmcnt(5)
	v_mfma_f32_16x16x32_bf16 v[68:71], v[230:233], v[226:229], v[68:71]
	s_waitcnt lgkmcnt(3)
	v_mfma_f32_16x16x32_bf16 v[84:87], v[248:251], v[234:237], v[84:87]
	s_waitcnt lgkmcnt(2)
	v_mfma_f32_16x16x32_bf16 v[72:75], v[248:251], v[238:241], v[72:75]
	s_waitcnt lgkmcnt(1)
	v_mfma_f32_16x16x32_bf16 v[80:83], v[248:251], v[242:245], v[80:83]
	s_waitcnt lgkmcnt(0)
	v_mfma_f32_16x16x32_bf16 v[68:71], v[248:251], v[76:79], v[68:71]
	s_movk_i32 s21, 0x200
	s_cmpk_lg_i32 s21, 0x200
	ds_read_b128 v[76:79], v191
	ds_read_b32 v194, v167
	ds_read_b32 v221, v168
	ds_read_b32 v222, v169
	ds_read_b32 v223, v170
	ds_read_b32 v224, v188
	s_waitcnt lgkmcnt(4)
	v_sub_f32_e32 v225, v76, v194
	v_exp_f32_e32 v225, v225
	v_sub_f32_e32 v226, v77, v194
	v_exp_f32_e32 v226, v226
	s_lshl_b32 s21, s20, 12
	v_mul_f32_e32 v84, v84, v225
	s_waitcnt lgkmcnt(3)
	v_mul_f32_e32 v84, v221, v84
	v_cvt_pk_bf16_f32 v84, v84, s0
	v_cndmask_b32_e64 v84, v84, 0, s[4:5]
	ds_write_b16 v192, v84
	v_mul_f32_e32 v84, v85, v226
	v_sub_f32_e32 v85, v78, v194
	v_exp_f32_e32 v85, v85
	v_mul_f32_e32 v84, v221, v84
	v_cvt_pk_bf16_f32 v84, v84, s0
	v_cndmask_b32_e64 v84, v84, 0, s[6:7]
	ds_write_b16 v192, v84 offset:144
	v_mul_f32_e32 v84, v86, v85
	v_sub_f32_e32 v85, v79, v194
	v_exp_f32_e32 v85, v85
	v_mul_f32_e32 v84, v221, v84
	v_cvt_pk_bf16_f32 v84, v84, s0
	v_cndmask_b32_e64 v84, v84, 0, s[8:9]
	ds_write_b16 v192, v84 offset:288
	v_mul_f32_e32 v84, v87, v85
	s_waitcnt lgkmcnt(5)
; __device__ __forceinline__ float ex2(float x) { return __builtin_amdgcn_exp2f(x); }
; template <int DK, int MODE>
; __device__ void rec_prompt_item(const Params& p, const int item, unsigned char* smem) {
;     ...
;     for (int x = 0; x < 2; ++x) {
;       const int fj = fe0 + x;
;       const int j = 16 * fj + l15;
;       const float cj = cumS[j], uj = uS[j];
; #pragma unroll
;       for (int r = 0; r < 4; ++r) {
;         const int i = 16 * fi + 4 * g + r;
;         float v = 0.f;
;         if (j <= i) v = sc[x][r] * ex2(ci[r] - cj) * uj;
;         *(u16*)(Ps + i * PS + j * 2) = f2bf(v);
;       }
;     }
;     {
;       const float atot = ex2(cumS[63]);
; #pragma unroll
;       for (int mf = 0; mf < MF; ++mf)
; #pragma unroll
;         for (int nf = 0; nf < 4; ++nf)
; #pragma unroll
;           for (int r = 0; r < 4; ++r) S[mf][nf][r] *= atot;
; #pragma unroll
;       for (int ks = 0; ks < 2; ++ks) {
;         bf16x8 af[MF], bfv[4];
; #pragma unroll
;         for (int mf = 0; mf < MF; ++mf) af[mf] = trfrag(Ks, QS, 32 * ks, dw + 16 * mf, lane);
; #pragma unroll
;         for (int nf = 0; nf < 4; ++nf) bfv[nf] = trfrag(Vts, VS, 32 * ks, 16 * nf, lane);
; #pragma unroll
;         for (int mf = 0; mf < MF; ++mf)
; #pragma unroll
;           for (int nf = 0; nf < 4; ++nf)
;             S[mf][nf] = __builtin_amdgcn_mfma_f32_16x16x32_bf16(af[mf], bfv[nf], S[mf][nf], 0, 0, 0);
;       }
;     }
;     __syncthreads();
	v_sub_f32_e32 v85, v76, v222
	v_mul_f32_e32 v84, v221, v84
	v_exp_f32_e32 v85, v85
	v_cvt_pk_bf16_f32 v84, v84, s0
	v_cndmask_b32_e64 v84, v84, 0, s[10:11]
	ds_write_b16 v192, v84 offset:432
	v_sub_f32_e32 v84, v77, v222
	v_mul_f32_e32 v80, v80, v85
	v_exp_f32_e32 v84, v84
	s_waitcnt lgkmcnt(5)
	v_mul_f32_e32 v80, v223, v80
	v_cvt_pk_bf16_f32 v80, v80, s0
	v_cndmask_b32_e64 v80, v80, 0, s[12:13]
	ds_write_b16 v193, v80
	v_mul_f32_e32 v80, v81, v84
	v_sub_f32_e32 v81, v78, v222
	v_exp_f32_e32 v81, v81
	v_mul_f32_e32 v80, v223, v80
	v_cvt_pk_bf16_f32 v80, v80, s0
	v_cndmask_b32_e64 v80, v80, 0, s[14:15]
	ds_write_b16 v193, v80 offset:144
	v_mul_f32_e32 v80, v82, v81
	v_sub_f32_e32 v81, v79, v222
	v_exp_f32_e32 v81, v81
	v_mul_f32_e32 v80, v223, v80
	v_cvt_pk_bf16_f32 v80, v80, s0
	v_cndmask_b32_e64 v80, v80, 0, s[16:17]
	ds_write_b16 v193, v80 offset:288
	v_mul_f32_e32 v80, v83, v81
	v_mul_f32_e32 v80, v223, v80
	v_cvt_pk_bf16_f32 v80, v80, s0
	v_cndmask_b32_e64 v80, v80, 0, s[18:19]
	ds_write_b16 v193, v80 offset:432
	s_waitcnt lgkmcnt(8)
	v_exp_f32_e32 v194, v224
	ds_read_b64_tr_b16 v[82:83], v195 offset:36992
	ds_read_b64_tr_b16 v[80:81], v195 offset:34816
	ds_read_b64_tr_b16 v[86:87], v195 offset:37024
	ds_read_b64_tr_b16 v[84:85], v195 offset:34848
	ds_read_b64_tr_b16 v[224:225], v196 offset:640
	ds_read_b64_tr_b16 v[222:223], v196
	ds_read_b64_tr_b16 v[226:227], v196 offset:32
	ds_read_b64_tr_b16 v[230:231], v196 offset:64
	ds_read_b64_tr_b16 v[234:235], v196 offset:96
	ds_read_b64_tr_b16 v[228:229], v196 offset:672
	ds_read_b64_tr_b16 v[232:233], v196 offset:704
	ds_read_b64_tr_b16 v[236:237], v196 offset:736
	s_add_u32 s44, s33, s21
	s_addc_u32 s45, s34, 0
	v_pk_mul_f32 v[66:67], v[66:67], v[194:195] op_sel_hi:[1,0]
	v_pk_mul_f32 v[64:65], v[64:65], v[194:195] op_sel_hi:[1,0]
	v_pk_mul_f32 v[62:63], v[62:63], v[194:195] op_sel_hi:[1,0]
	v_pk_mul_f32 v[60:61], v[60:61], v[194:195] op_sel_hi:[1,0]
	v_pk_mul_f32 v[58:59], v[58:59], v[194:195] op_sel_hi:[1,0]
	v_pk_mul_f32 v[56:57], v[56:57], v[194:195] op_sel_hi:[1,0]
	v_pk_mul_f32 v[54:55], v[54:55], v[194:195] op_sel_hi:[1,0]
	v_pk_mul_f32 v[52:53], v[52:53], v[194:195] op_sel_hi:[1,0]
	v_pk_mul_f32 v[50:51], v[50:51], v[194:195] op_sel_hi:[1,0]
	v_pk_mul_f32 v[48:49], v[48:49], v[194:195] op_sel_hi:[1,0]
	v_pk_mul_f32 v[42:43], v[42:43], v[194:195] op_sel_hi:[1,0]
	v_pk_mul_f32 v[40:41], v[40:41], v[194:195] op_sel_hi:[1,0]
	v_pk_mul_f32 v[38:39], v[38:39], v[194:195] op_sel_hi:[1,0]
	v_pk_mul_f32 v[36:37], v[36:37], v[194:195] op_sel_hi:[1,0]
	v_pk_mul_f32 v[46:47], v[46:47], v[194:195] op_sel_hi:[1,0]
	v_pk_mul_f32 v[44:45], v[44:45], v[194:195] op_sel_hi:[1,0]
	s_waitcnt lgkmcnt(6)
	v_mfma_f32_16x16x32_bf16 v[64:67], v[80:83], v[222:225], v[64:67]
	v_lshlrev_b32_e32 v194, 16, v216
	v_mul_f32_e32 v216, 0xbfb8aa3b, v194
	v_exp_f32_e32 v216, v216
	s_waitcnt lgkmcnt(2)
	v_mfma_f32_16x16x32_bf16 v[60:63], v[80:83], v[226:229], v[60:63]
	s_waitcnt lgkmcnt(1)
	v_mfma_f32_16x16x32_bf16 v[56:59], v[80:83], v[230:233], v[56:59]
	s_waitcnt lgkmcnt(0)
	v_mfma_f32_16x16x32_bf16 v[52:55], v[80:83], v[234:237], v[52:55]
	v_mfma_f32_16x16x32_bf16 v[48:51], v[84:87], v[222:225], v[48:51]
	v_mfma_f32_16x16x32_bf16 v[40:43], v[84:87], v[226:229], v[40:43]
	v_mfma_f32_16x16x32_bf16 v[36:39], v[84:87], v[230:233], v[36:39]
	v_mfma_f32_16x16x32_bf16 v[80:83], v[84:87], v[234:237], v[44:47]
	s_nop 2
	ds_read_b64_tr_b16 v[46:47], v197 offset:36992
	ds_read_b64_tr_b16 v[44:45], v197 offset:34816
	ds_read_b64_tr_b16 v[86:87], v197 offset:37024
	ds_read_b64_tr_b16 v[84:85], v197 offset:34848
	ds_read_b64_tr_b16 v[224:225], v196 offset:5760
	ds_read_b64_tr_b16 v[222:223], v196 offset:5120
	ds_read_b64_tr_b16 v[226:227], v196 offset:5152
	ds_read_b64_tr_b16 v[230:231], v196 offset:5184
	ds_read_b64_tr_b16 v[234:235], v196 offset:5216
	ds_read_b64_tr_b16 v[228:229], v196 offset:5792
	ds_read_b64_tr_b16 v[232:233], v196 offset:5824
	ds_read_b64_tr_b16 v[236:237], v196 offset:5856
	s_waitcnt lgkmcnt(0)
	s_barrier
; template <int DK, int MODE>
; __device__ void rec_prompt_item(const Params& p, const int item, unsigned char* smem) {
;     ...
;         for (int mf = 0; mf < MF; ++mf) af[mf] = trfrag(Ks, QS, 32 * ks, dw + 16 * mf, lane);
; #pragma unroll
;         for (int nf = 0; nf < 4; ++nf) bfv[nf] = trfrag(Vts, VS, 32 * ks, 16 * nf, lane);
; #pragma unroll
;         for (int mf = 0; mf < MF; ++mf)
; #pragma unroll
;           for (int nf = 0; nf < 4; ++nf)
;             S[mf][nf] = __builtin_amdgcn_mfma_f32_16x16x32_bf16(af[mf], bfv[nf], S[mf][nf], 0, 0, 0);
;       }
;     }
;     __syncthreads();
;     f32x4 in[2];
; #pragma unroll
;     for (int x = 0; x < 2; ++x) in[x] = (f32x4){0.f, 0.f, 0.f, 0.f};
; #pragma unroll
;     for (int ks = 0; ks < 2; ++ks) {
;       const bf16x8 a = *(const bf16x8*)(Ps + (16 * fi + l15) * PS + ks * 64 + g * 16);
;       bf16x8 bv[2];
; #pragma unroll
;       for (int x = 0; x < 2; ++x) bv[x] = trfrag(Vs, VS, 32 * ks, 16 * (fe0 + x), lane);
; #pragma unroll
;       for (int x = 0; x < 2; ++x) in[x] = __builtin_amdgcn_mfma_f32_16x16x32_bf16(a, bv[x], in[x], 0, 0, 0);
;     }
;     {
;       float ss[4] = {0.f, 0.f, 0.f, 0.f};
;       u16* aout = (u16*)(p.ws + OFF_A2);
;       float* parts = (float*)(p.ws + OFF_PARTS);
; #pragma unroll
;       for (int x = 0; x < 2; ++x) {
;         const int e = 16 * (fe0 + x) + l15;
;         const float gn = gnv[x];
;         const int ocol = (MODE == 0) ? (h * 512 + s * 64 + e) : (h * 64 + e);
; #pragma unroll
;         for (int r = 0; r < 4; ++r) {
;           const int i = 16 * fi + 4 * g + r;
;           float o = in[x][r] + cr[x][r] * ex2(ci[r]);
;           const float gv = bf2f(gzc[x][r]);
;           float val;
;           if (MODE == 0) {
;             ss[r] += o * o;
;             val = o * gn * silu(gv);
;           } else {
;             const float xs = bf2f(*(const u16*)(Vs + i * VS + e * 2));
;             const float y = o + xs * dsk;
;             const float gg = y * silu(gv);
;             ss[r] += gg * gg;
;             val = gg * gn;
;           }
;           *(u16*)((char*)aout + (size_t)r0 * 4096 + 32 * x + aoff[r]) = f2bf(val);
;         }
;       }
; #pragma unroll
;       for (int r = 0; r < 4; ++r) {
;         const float v = row16_sum(ss[r]);
;         if (l15 == 0) {
;           const int i = 16 * fi + 4 * g + r;
	v_mfma_f32_16x16x32_bf16 v[64:67], v[44:47], v[222:225], v[64:67]
	v_mfma_f32_16x16x32_bf16 v[60:63], v[44:47], v[226:229], v[60:63]
	v_mfma_f32_16x16x32_bf16 v[56:59], v[44:47], v[230:233], v[56:59]
	v_mfma_f32_16x16x32_bf16 v[52:55], v[44:47], v[234:237], v[52:55]
	v_mfma_f32_16x16x32_bf16 v[48:51], v[84:87], v[222:225], v[48:51]
	v_mfma_f32_16x16x32_bf16 v[44:47], v[84:87], v[226:229], v[40:43]
	ds_read_b128 v[222:225], v198
	ds_read_b64_tr_b16 v[226:227], v217
	ds_read_b64_tr_b16 v[228:229], v217 offset:640
	v_mfma_f32_16x16x32_bf16 v[40:43], v[84:87], v[230:233], v[36:39]
	v_mfma_f32_16x16x32_bf16 v[36:39], v[84:87], v[234:237], v[80:83]
	s_nop 2
	ds_read_b64_tr_b16 v[80:81], v218
	ds_read_b64_tr_b16 v[82:83], v218 offset:640
	ds_read_b128 v[84:87], v198 offset:64
	s_waitcnt lgkmcnt(3)
	v_mfma_f32_16x16x32_bf16 v[226:229], v[222:225], v[226:229], 0
	s_waitcnt lgkmcnt(1)
	v_mfma_f32_16x16x32_bf16 v[222:225], v[222:225], v[80:83], 0
	ds_read_b64_tr_b16 v[80:81], v219
	ds_read_b64_tr_b16 v[82:83], v219 offset:640
	ds_read_b64_tr_b16 v[218:219], v220
	ds_read_b64_tr_b16 v[220:221], v220 offset:640
	s_waitcnt lgkmcnt(2)
	v_mfma_f32_16x16x32_bf16 v[80:83], v[84:87], v[80:83], v[226:229]
	s_waitcnt lgkmcnt(0)
	v_mfma_f32_16x16x32_bf16 v[84:87], v[84:87], v[218:221], v[222:225]
	s_waitcnt vmcnt(15)
	ds_write_b128 v181, v[4:7]
	ds_write_b128 v181, v[0:3] offset:34816
	s_waitcnt vmcnt(13)
	ds_write_b128 v182, v[12:15]
	ds_write_b128 v182, v[8:11] offset:34816
	s_waitcnt vmcnt(11)
	ds_write_b128 v183, v[20:23]
	ds_write_b128 v183, v[16:19] offset:34816
	s_waitcnt vmcnt(9)
	ds_write_b128 v184, v[32:35]
	ds_write_b128 v184, v[24:27] offset:34816
	v_exp_f32_e32 v218, v76
	v_add_f32_e32 v76, 1.0, v216
	v_rcp_f32_e32 v76, v76
	v_lshl_add_u64 v[216:217], s[44:45], 0, v[134:135]
	s_nop 1
	v_fma_f32 v219, v72, v218, v80
	v_mul_f32_e32 v72, v117, v219
	v_mul_f32_e32 v76, v76, v194
	v_mul_f32_e32 v72, v76, v72
	v_lshlrev_b32_e32 v76, 16, v215
	v_mul_f32_e32 v80, 0xbfb8aa3b, v76
	v_exp_f32_e32 v80, v80
	v_exp_f32_e32 v194, v77
	v_cvt_pk_bf16_f32 v72, v72, s0
	global_store_short v[216:217], v72, off
	v_add_f32_e32 v77, 1.0, v80
	v_rcp_f32_e32 v77, v77
	v_fma_f32 v73, v73, v194, v81
	v_mul_f32_e32 v72, v117, v73
	v_lshlrev_b32_e32 v80, 16, v214
	v_mul_f32_e32 v76, v77, v76
	v_mul_f32_e32 v72, v76, v72
	v_mul_f32_e32 v76, 0xbfb8aa3b, v80
	v_exp_f32_e32 v81, v76
	v_exp_f32_e32 v214, v78
	v_cvt_pk_bf16_f32 v72, v72, s0
	v_lshl_add_u64 v[76:77], s[44:45], 0, v[136:137]
	v_add_f32_e32 v78, 1.0, v81
	v_rcp_f32_e32 v78, v78
	global_store_short v[76:77], v72, off
	v_fma_f32 v72, v74, v214, v82
	v_mul_f32_e32 v74, v117, v72
	v_mul_f32_e32 v78, v78, v80
	v_mul_f32_e32 v74, v78, v74
	v_lshlrev_b32_e32 v78, 16, v213
	v_mul_f32_e32 v80, 0xbfb8aa3b, v78
	v_exp_f32_e32 v82, v80
	v_exp_f32_e32 v213, v79
	v_cvt_pk_bf16_f32 v74, v74, s0
	v_lshl_add_u64 v[80:81], s[44:45], 0, v[138:139]
	v_add_f32_e32 v79, 1.0, v82
	v_rcp_f32_e32 v79, v79
	v_fmac_f32_e32 v83, v75, v213
	global_store_short v[80:81], v74, off
	v_mul_f32_e32 v74, v117, v83
	v_mul_f32_e32 v75, v79, v78
	v_mul_f32_e32 v74, v75, v74
	v_cvt_pk_bf16_f32 v74, v74, s0
	v_lshl_add_u64 v[78:79], s[44:45], 0, v[140:141]
	global_store_short v[78:79], v74, off
	v_lshlrev_b32_e32 v74, 16, v212
	v_mul_f32_e32 v75, 0xbfb8aa3b, v74
	v_exp_f32_e32 v75, v75
	v_fma_f32 v68, v68, v218, v84
	v_lshlrev_b32_e32 v84, 16, v211
	v_mul_f32_e32 v211, 0xbfb8aa3b, v84
	v_add_f32_e32 v75, 1.0, v75
	v_rcp_f32_e32 v75, v75
	v_exp_f32_e32 v211, v211
	v_mul_f32_e32 v82, v68, v68
	v_mul_f32_e32 v68, v199, v68
	v_mul_f32_e32 v74, v75, v74
	v_mul_f32_e32 v68, v74, v68
	v_add_f32_e32 v74, 1.0, v211
	v_rcp_f32_e32 v75, v74
	v_cvt_pk_bf16_f32 v68, v68, s0
	v_fma_f32 v74, v69, v194, v85
	global_store_short v[216:217], v68, off offset:32
	v_mul_f32_e32 v68, v199, v74
	v_mul_f32_e32 v69, v75, v84
	v_mul_f32_e32 v68, v69, v68
	v_lshlrev_b32_e32 v69, 16, v210
	v_mul_f32_e32 v75, 0xbfb8aa3b, v69
	v_exp_f32_e32 v75, v75
	v_cvt_pk_bf16_f32 v68, v68, s0
	global_store_short v[76:77], v68, off offset:32
	v_lshlrev_b32_e32 v76, 16, v209
	v_add_f32_e32 v75, 1.0, v75
	v_rcp_f32_e32 v75, v75
	v_mul_f32_e32 v77, 0xbfb8aa3b, v76
	v_exp_f32_e32 v77, v77
	v_fma_f32 v70, v70, v214, v86
	v_mul_f32_e32 v68, v199, v70
	v_mul_f32_e32 v69, v75, v69
	v_mul_f32_e32 v68, v69, v68
	v_add_f32_e32 v69, 1.0, v77
	v_rcp_f32_e32 v69, v69
	v_cvt_pk_bf16_f32 v68, v68, s0
	v_fmac_f32_e32 v87, v71, v213
	v_fmac_f32_e32 v82, v219, v219
	global_store_short v[80:81], v68, off offset:32
	v_mul_f32_e32 v68, v199, v87
	v_mul_f32_e32 v69, v69, v76
	v_mul_f32_e32 v68, v69, v68
	v_cvt_pk_bf16_f32 v68, v68, s0
	v_add_f32_dpp v69, v82, v82 quad_perm:[1,0,3,2] row_mask:0xf bank_mask:0xf bound_ctrl:1
	global_store_short v[78:79], v68, off offset:32
	v_add_u32_e32 v68, s20, v91
	v_add_f32_dpp v69, v69, v69 quad_perm:[2,3,0,1] row_mask:0xf bank_mask:0xf bound_ctrl:1
	s_nop 1
	v_add_f32_dpp v71, v69, v69 row_ror:4 row_mask:0xf bank_mask:0xf bound_ctrl:1
	s_nop 1
	v_mov_b32_dpp v75, v71 row_ror:8 row_mask:0xf bank_mask:0xf bound_ctrl:1
	s_and_saveexec_b64 s[20:21], s[2:3]
	s_cbranch_execz .LBB0_440
	v_ashrrev_i32_e32 v69, 31, v68
	v_lshlrev_b64 v[76:77], 8, v[68:69]
	v_lshl_add_u64 v[76:77], v[144:145], 0, v[76:77]
	v_add_f32_e32 v69, v71, v75
	global_store_dword v[76:77], v69, off
